# fix: prefetched-tile wait in the in-proj top block is vmcnt(8) (the 16-byte-store epilogue issues only 8/16 stores after the 8 prefetch loads, so vmcnt(63) no longer covered them)
# baseline (speedup 1.0000x reference)
; #define G8_WV(n) asm volatile("s_waitcnt vmcnt(" #n ")" ::: "memory")
; #define G8_BAR __builtin_amdgcn_s_barrier()
; DI void gemm8p(const u16* __restrict__ A, const u16* __restrict__ Bt, int brow, int bcol, f32x4 (&acc)[2][2][4][2]) {
;     ...
;   G8_STAGE(G8_SB(0, 0), Bt, bcol, 0); G8_STAGE(G8_SA(0, 0), A, brow, 0);
;   G8_STAGE(G8_SB(0, 1), Bt, bcol + HALF, 0); G8_STAGE(G8_SA(0, 1), A, brow + HALF, 0);
;   if (wr == 1) G8_BAR;
;   G8_WV(4); G8_BAR;
;   G8_STAGE(G8_SB(1, 0), Bt, bcol, 1); G8_STAGE(G8_SA(1, 0), A, brow, 1); G8_STAGE(G8_SB(1, 1), Bt, bcol + HALF, 1);
;   G8_WV(6); G8_BAR;
.Lipf_w4h:
	s_waitcnt vmcnt(8)
